# KP table loop: second trip balanced over all 187 table workgroups
# baseline (speedup 1.0000x reference)
; __device__ __forceinline__ unsigned pk2(float lo, float hi) { f32x2_t v = {lo, hi}; bf16x2_t b = __builtin_convertvector(v, bf16x2_t); return __builtin_bit_cast(unsigned, b); }
; __device__ __forceinline__ void p1_tables(ArgsRef A, int tid, int first_block) {
;     ...
;       for (int i = gt; i < 32 * 64 * 64; i += NGT) { const int ln = i & 63, j = (i >> 6) & 63, g = i >> 12; const int c = ln & 15, kq = ln >> 4, jj = j - (kq >> 1), c0 = 8 * (kq & 1);
;         float acc[8];
; #pragma unroll
;         for (int k = 0; k < 8; ++k) acc[k] = 0.f;
;         if (jj >= 0) { const float* pw = PW + (size_t)((g * 65 + jj) * 64) * 2; const float* cr = Cre + (g * 16 + c) * 64; const float* ci = Cim + (g * 16 + c) * 64; const float* bb = BB + (size_t)(g * 64) * 32 + c0 * 2;
; #pragma unroll 4
;             for (int p = 0; p < 64; ++p) { const float xr = cr[p] * pw[2 * p] - ci[p] * pw[2 * p + 1], xi = cr[p] * pw[2 * p + 1] + ci[p] * pw[2 * p]; const f32x4* b4 = (const f32x4*)(bb + p * 32);
; #pragma unroll
;                 for (int k = 0; k < 4; ++k) { const f32x4 q = b4[k]; acc[2 * k] += xr * q.x - xi * q.y; acc[2 * k + 1] += xr * q.z - xi * q.w; } } }
;         u32x4 o; o.x = pk2(acc[0], acc[1]); o.y = pk2(acc[2], acc[3]); o.z = pk2(acc[4], acc[5]); o.w = pk2(acc[6], acc[7]);
;         *(u32x4*)(KP + (size_t)i * 8) = o; } }
.LBB0_163:
	s_or_b64 exec, exec, s[36:37]
	v_ashrrev_i32_e32 v1, 31, v0
	v_cvt_pk_bf16_f32 v7, v2, v3
	v_lshl_add_u64 v[2:3], v[0:1], 4, s[30:31]
	s_cmp_lg_u32 s1, 0x17600
	s_cbranch_scc1 .Lkp_step_orig
	s_movk_i32 s4, 0xbb
	v_mov_b32_e32 v110, 0x20000
	v_lshrrev_b32_e32 v111, 9, v0
	v_bfe_u32 v112, v0, 6, 3
	v_mad_u32_u24 v111, v112, s4, v111
	v_and_b32_e32 v112, 63, v0
	v_add_u32_e32 v113, 0x5d8, v111
	v_lshl_or_b32 v113, v113, 6, v112
	v_cmp_gt_u32_e32 vcc, 0x228, v111
	s_nop 1
	v_cndmask_b32_e32 v113, v110, v113, vcc
	v_cmp_gt_u32_e32 vcc, 0x17600, v0
	s_nop 1
	v_cndmask_b32_e32 v0, v110, v113, vcc
	v_lshlrev_b32_e32 v24, 6, v0
	s_branch .Lkp_step_done
.Lkp_step_orig:
	v_add_u32_e32 v0, s1, v0
	v_add_u32_e32 v24, s3, v24
.Lkp_step_done:
	s_mov_b32 s4, 0x1ffff
	v_cmp_lt_i32_e32 vcc, s4, v0
	v_cvt_pk_bf16_f32 v4, v10, v11
	v_cvt_pk_bf16_f32 v5, v12, v13
	v_cvt_pk_bf16_f32 v6, v8, v9
	s_or_b64 s[34:35], vcc, s[34:35]
	global_store_dwordx4 v[2:3], v[4:7], off
	s_andn2_b64 exec, exec, s[34:35]
	s_cbranch_execz .LBB0_167
